# in-proj GEMM: first K-loop iteration peeled with C=0 for the loop-carried accumulator reads; per-unit 128 v_mov zeroing removed
# baseline (speedup 1.0000x reference)
; #define G8_STAGE(bufoff, gbase, voff) do { const char* _gb = uptr((const char*)(gbase)); _Pragma("unroll") for (int _i = 0; _i < 2; ++_i) \
;         __builtin_amdgcn_global_load_lds((const unsigned*)(_gb + (voff)[_i]), (LAS unsigned*)(lds + (bufoff) + ldsw + _i * 8192), 16, 0, 0); } while (0)
; #define G8_LDA(dst, b, h) do { _Pragma("unroll") for (int m = 0; m < 4; ++m) _Pragma("unroll") for (int k = 0; k < 2; ++k) dst[m][k] = *(const LAS bf16x8*)(lds + G8_SA(b, h) + aoff + m * 2048 + k * 1024); } while (0)
; #define G8_LDB(dst, b, h) do { _Pragma("unroll") for (int n = 0; n < 2; ++n) _Pragma("unroll") for (int k = 0; k < 2; ++k) dst[n][k] = *(const LAS bf16x8*)(lds + G8_SB(b, h) + boff + n * 2048 + k * 1024); } while (0)
; #define G8_MMA(ai, bj, At, Bt_) do { __builtin_amdgcn_s_setprio(1); _Pragma("unroll") for (int m = 0; m < 4; ++m) _Pragma("unroll") for (int n = 0; n < 2; ++n) _Pragma("unroll") for (int k = 0; k < 2; ++k) \
;         acc[ai][bj][m][n] = __builtin_amdgcn_mfma_f32_16x16x32_bf16(Bt_[n][k], At[m][k], acc[ai][bj][m][n], 0, 0, 0); __builtin_amdgcn_s_setprio(0); } while (0)
; #define G8_WAIT_L(n) asm volatile("s_waitcnt lgkmcnt(" #n ")" ::: "memory")
; #define G8_BAR __builtin_amdgcn_s_barrier()
;     ...
;         const bool has_next = next_unit<NKH, ROT>(ui + 1, nM, nN, nxt);
;         const char* nA = uptr(has_next ? (const char*)A + (size_t)nxt.pm * tstepA + (size_t)nxt.kh * kchunk + E.a_off(nxt.pn) : cA);
;         const char* nB = uptr(has_next ? (const char*)Bt + (size_t)nxt.pn * tstepB + (size_t)nxt.kh * kchunk : cB);
;         for (int t = 0; t < nt; t += 2) {
;             const bool last = (t == nt - 2);
;             const char* a1 = cA + (size_t)(t + 1) * kstep;
;             const char* a2 = last ? nA : cA + (size_t)(t + 2) * kstep; const char* b2 = last ? nB : cB + (size_t)(t + 2) * kstep;
;             const char* a3 = a2 + kstep; const char* b3 = b2 + kstep;
;             G8_LDB(B0, 0, 0); G8_SCHED; G8_LDA(At, 0, 0); G8_STAGE(G8_SA(1, 1), a1 + hstepA, voffA);
;             G8_WAIT_L(8); G8_BAR; G8_WAIT_L(0); G8_MMA(0, 0, At, B0); G8_BAR; G8_SCHED;
;             G8_LDB(B1, 0, 1); G8_STAGE(G8_SB(0, 0), b2, voffB);
;             G8_BAR; G8_WAIT_L(0); G8_MMA(0, 1, At, B1); G8_BAR;
;             G8_LDA(At, 0, 1); G8_STAGE(G8_SA(0, 0), a2, voffA);
;             G8_BAR; G8_WAIT_L(0); G8_MMA(1, 0, At, B0); G8_BAR; G8_SCHED;
.LBB0_187:
	s_ashr_i32 s29, s28, 31
	v_cmp_lt_u64_e32 vcc, s[12:13], v[200:201]
	s_lshl_b64 s[12:13], s[28:29], 19
	v_readlane_b32 s7, v255, 13
	s_add_u32 s7, s7, s12
	v_readlane_b32 s9, v255, 14
	s_addc_u32 s9, s9, s13
	s_and_b64 s[12:13], vcc, exec
	s_cselect_b32 s34, s7, s2
	s_cselect_b32 s35, s9, s3
	s_ashr_i32 s31, s30, 31
	s_lshl_b64 s[12:13], s[30:31], 19
	s_add_u32 s7, s43, s12
	s_addc_u32 s9, s44, s13
	s_and_b64 s[12:13], vcc, exec
	s_cselect_b32 s36, s7, s10
	s_cselect_b32 s37, s9, s11
	s_add_u32 s7, s10, 0x100
	s_addc_u32 s9, s11, 0
	s_add_u32 s2, s2, 0x40080
	s_addc_u32 s3, s3, 0
	s_mov_b32 s16, -2
	s_waitcnt vmcnt(0)
	ds_read_b128 v[48:51], v240
	ds_read_b128 v[52:55], v240 offset:1024
	ds_read_b128 v[72:75], v240 offset:2048
	ds_read_b128 v[76:79], v240 offset:3072
	s_add_u32 s10, s2, 0xfffc0080
	s_addc_u32 s11, s3, -1
	s_cmp_eq_u32 s16, 12
	s_cselect_b32 s14, s34, s10
	s_cselect_b32 s15, s35, s11
	s_cselect_b32 s10, s36, s7
	s_cselect_b32 s11, s37, s9
	s_add_u32 s12, s14, 0x80
	s_addc_u32 s13, s15, 0
	v_lshl_add_u64 v[176:177], s[2:3], 0, v[192:193]
	s_add_i32 m0, s46, 0xc000
	ds_read_b128 v[88:91], v241
	ds_read_b128 v[100:103], v241 offset:1024
	ds_read_b128 v[112:115], v241 offset:2048
	ds_read_b128 v[124:127], v241 offset:3072
	ds_read_b128 v[136:139], v241 offset:4096
	ds_read_b128 v[140:143], v241 offset:5120
	ds_read_b128 v[160:163], v241 offset:6144
	ds_read_b128 v[164:167], v241 offset:7168
	global_load_lds_dwordx4 v[176:177], off
	v_lshl_add_u64 v[176:177], s[2:3], 0, v[196:197]
	s_add_i32 m0, s46, 0xe000
	s_nop 0
	global_load_lds_dwordx4 v[176:177], off
	s_waitcnt lgkmcnt(8)
	s_barrier
	s_waitcnt lgkmcnt(0)
	s_setprio 1
	s_waitcnt lgkmcnt(0)
	v_mfma_f32_16x16x32_bf16 v[172:175], v[48:51], v[88:91], 0
	v_mfma_f32_16x16x32_bf16 v[168:171], v[72:75], v[88:91], 0
	v_mfma_f32_16x16x32_bf16 v[148:151], v[48:51], v[112:115], 0
	v_mfma_f32_16x16x32_bf16 v[144:147], v[72:75], v[112:115], 0
	v_mfma_f32_16x16x32_bf16 v[120:123], v[48:51], v[136:139], 0
	v_mfma_f32_16x16x32_bf16 v[116:119], v[72:75], v[136:139], 0
	v_mfma_f32_16x16x32_bf16 v[96:99], v[48:51], v[160:163], 0
	v_mfma_f32_16x16x32_bf16 v[92:95], v[72:75], v[160:163], 0
	v_mfma_f32_16x16x32_bf16 v[172:175], v[52:55], v[100:103], v[172:175]
	v_mfma_f32_16x16x32_bf16 v[168:171], v[76:79], v[100:103], v[168:171]
	v_mfma_f32_16x16x32_bf16 v[148:151], v[52:55], v[124:127], v[148:151]
	v_mfma_f32_16x16x32_bf16 v[144:147], v[76:79], v[124:127], v[144:147]
	v_mfma_f32_16x16x32_bf16 v[120:123], v[52:55], v[140:143], v[120:123]
	v_mfma_f32_16x16x32_bf16 v[116:119], v[76:79], v[140:143], v[116:119]
	v_mfma_f32_16x16x32_bf16 v[96:99], v[52:55], v[164:167], v[96:99]
	v_mfma_f32_16x16x32_bf16 v[92:95], v[76:79], v[164:167], v[92:95]
	s_setprio 0
	s_barrier
	s_add_i32 s17, s57, s45
	v_lshl_add_u64 v[206:207], s[10:11], 0, v[194:195]
	s_mov_b32 m0, s17
	ds_read_b128 v[176:179], v242
	ds_read_b128 v[180:183], v242 offset:1024
	ds_read_b128 v[184:187], v242 offset:2048
	ds_read_b128 v[188:191], v242 offset:3072
	global_load_lds_dwordx4 v[206:207], off
	v_lshl_add_u64 v[206:207], s[10:11], 0, v[198:199]
	s_add_i32 m0, s17, 0x2000
	s_nop 0
	global_load_lds_dwordx4 v[206:207], off
	s_barrier
	s_waitcnt lgkmcnt(0)
	s_setprio 1
	s_waitcnt lgkmcnt(0)
	v_mfma_f32_16x16x32_bf16 v[156:159], v[176:179], v[88:91], 0
	v_mfma_f32_16x16x32_bf16 v[88:91], v[184:187], v[88:91], 0
	v_mfma_f32_16x16x32_bf16 v[108:111], v[176:179], v[136:139], 0
	v_mfma_f32_16x16x32_bf16 v[104:107], v[184:187], v[136:139], 0
	v_mfma_f32_16x16x32_bf16 v[84:87], v[176:179], v[160:163], 0
	v_mfma_f32_16x16x32_bf16 v[80:83], v[184:187], v[160:163], 0
	v_mfma_f32_16x16x32_bf16 v[156:159], v[180:183], v[100:103], v[156:159]
	v_mfma_f32_16x16x32_bf16 v[88:91], v[188:191], v[100:103], v[88:91]
	v_mfma_f32_16x16x32_bf16 v[100:103], v[176:179], v[112:115], 0
	v_mfma_f32_16x16x32_bf16 v[112:115], v[184:187], v[112:115], 0
	v_mfma_f32_16x16x32_bf16 v[108:111], v[180:183], v[140:143], v[108:111]
	v_mfma_f32_16x16x32_bf16 v[104:107], v[188:191], v[140:143], v[104:107]
	v_mfma_f32_16x16x32_bf16 v[84:87], v[180:183], v[164:167], v[84:87]
	v_mfma_f32_16x16x32_bf16 v[80:83], v[188:191], v[164:167], v[80:83]
	v_mfma_f32_16x16x32_bf16 v[100:103], v[180:183], v[124:127], v[100:103]
	v_mfma_f32_16x16x32_bf16 v[112:115], v[188:191], v[124:127], v[112:115]
	s_setprio 0
	s_mov_b32 m0, s46
	v_lshl_add_u64 v[206:207], s[14:15], 0, v[192:193]
	s_barrier
	ds_read_b128 v[124:127], v241 offset:16384
	ds_read_b128 v[128:131], v241 offset:17408
	ds_read_b128 v[132:135], v241 offset:18432
	ds_read_b128 v[136:139], v241 offset:19456
	ds_read_b128 v[140:143], v241 offset:20480
	ds_read_b128 v[152:155], v241 offset:21504
	ds_read_b128 v[160:163], v241 offset:22528
	ds_read_b128 v[164:167], v241 offset:23552
	global_load_lds_dwordx4 v[206:207], off
	v_lshl_add_u64 v[206:207], s[14:15], 0, v[196:197]
	s_mov_b32 m0, s47
	s_nop 0
	global_load_lds_dwordx4 v[206:207], off
	s_barrier
	s_waitcnt lgkmcnt(0)
	s_setprio 1
	s_waitcnt lgkmcnt(0)
	v_mfma_f32_16x16x32_bf16 v[68:71], v[48:51], v[124:127], 0
	v_mfma_f32_16x16x32_bf16 v[64:67], v[72:75], v[124:127], 0
	v_mfma_f32_16x16x32_bf16 v[44:47], v[48:51], v[132:135], 0
	v_mfma_f32_16x16x32_bf16 v[40:43], v[72:75], v[132:135], 0
	v_mfma_f32_16x16x32_bf16 v[28:31], v[48:51], v[140:143], 0
	v_mfma_f32_16x16x32_bf16 v[24:27], v[72:75], v[140:143], 0
	v_mfma_f32_16x16x32_bf16 v[12:15], v[48:51], v[160:163], 0
	v_mfma_f32_16x16x32_bf16 v[8:11], v[72:75], v[160:163], 0
	v_mfma_f32_16x16x32_bf16 v[68:71], v[52:55], v[128:131], v[68:71]
	v_mfma_f32_16x16x32_bf16 v[64:67], v[76:79], v[128:131], v[64:67]
	v_mfma_f32_16x16x32_bf16 v[44:47], v[52:55], v[136:139], v[44:47]
	v_mfma_f32_16x16x32_bf16 v[40:43], v[76:79], v[136:139], v[40:43]
	v_mfma_f32_16x16x32_bf16 v[28:31], v[52:55], v[152:155], v[28:31]
	v_mfma_f32_16x16x32_bf16 v[24:27], v[76:79], v[152:155], v[24:27]
	v_mfma_f32_16x16x32_bf16 v[12:15], v[52:55], v[164:167], v[12:15]
	v_mfma_f32_16x16x32_bf16 v[8:11], v[76:79], v[164:167], v[8:11]
	s_setprio 0
	s_barrier
; #define G8_STAGE(bufoff, gbase, voff) do { const char* _gb = uptr((const char*)(gbase)); _Pragma("unroll") for (int _i = 0; _i < 2; ++_i) \
;         __builtin_amdgcn_global_load_lds((const unsigned*)(_gb + (voff)[_i]), (LAS unsigned*)(lds + (bufoff) + ldsw + _i * 8192), 16, 0, 0); } while (0)
; #define G8_LDA(dst, b, h) do { _Pragma("unroll") for (int m = 0; m < 4; ++m) _Pragma("unroll") for (int k = 0; k < 2; ++k) dst[m][k] = *(const LAS bf16x8*)(lds + G8_SA(b, h) + aoff + m * 2048 + k * 1024); } while (0)
; #define G8_LDB(dst, b, h) do { _Pragma("unroll") for (int n = 0; n < 2; ++n) _Pragma("unroll") for (int k = 0; k < 2; ++k) dst[n][k] = *(const LAS bf16x8*)(lds + G8_SB(b, h) + boff + n * 2048 + k * 1024); } while (0)
; #define G8_MMA(ai, bj, At, Bt_) do { __builtin_amdgcn_s_setprio(1); _Pragma("unroll") for (int m = 0; m < 4; ++m) _Pragma("unroll") for (int n = 0; n < 2; ++n) _Pragma("unroll") for (int k = 0; k < 2; ++k) \
;         acc[ai][bj][m][n] = __builtin_amdgcn_mfma_f32_16x16x32_bf16(Bt_[n][k], At[m][k], acc[ai][bj][m][n], 0, 0, 0); __builtin_amdgcn_s_setprio(0); } while (0)
; #define G8_WAIT_V(n) asm volatile("s_waitcnt vmcnt(" #n ")" ::: "memory")
; #define G8_WAIT_L(n) asm volatile("s_waitcnt lgkmcnt(" #n ")" ::: "memory")
; #define G8_BAR __builtin_amdgcn_s_barrier()
; #define G8_SCHED __builtin_amdgcn_sched_barrier(0)
;     ...
;             G8_STAGE(G8_SB(0, 1), b2 + hstepB, voffB);
;             G8_WAIT_V(6); G8_BAR; G8_MMA(1, 1, At, B1); G8_BAR;
;             G8_LDB(B0, 1, 0); G8_SCHED; G8_LDA(At, 1, 0); G8_STAGE(G8_SA(0, 1), a2 + hstepA, voffA);
;             G8_WAIT_L(8); G8_BAR; G8_WAIT_L(0); G8_MMA(0, 0, At, B0); G8_BAR; G8_SCHED;
;             G8_LDB(B1, 1, 1); G8_STAGE(G8_SB(1, 0), b3, voffB);
;             G8_BAR; G8_WAIT_L(0); G8_MMA(0, 1, At, B1); G8_BAR;
;             G8_LDA(At, 1, 1); G8_STAGE(G8_SA(1, 0), a3, voffA);
	s_add_u32 s38, s10, 0x40000
	s_addc_u32 s39, s11, 0
	s_add_i32 s17, s58, s45
	v_lshl_add_u64 v[48:49], s[38:39], 0, v[194:195]
	s_mov_b32 m0, s17
	s_nop 0
	global_load_lds_dwordx4 v[48:49], off
	v_lshl_add_u64 v[48:49], s[38:39], 0, v[198:199]
	s_add_i32 m0, s17, 0x2000
	s_nop 0
	global_load_lds_dwordx4 v[48:49], off
	s_waitcnt vmcnt(6)
	s_barrier
	s_setprio 1
	v_mfma_f32_16x16x32_bf16 v[36:39], v[176:179], v[132:135], 0
	v_mfma_f32_16x16x32_bf16 v[32:35], v[184:187], v[132:135], 0
	v_mfma_f32_16x16x32_bf16 v[20:23], v[176:179], v[140:143], 0
	v_mfma_f32_16x16x32_bf16 v[16:19], v[184:187], v[140:143], 0
	v_mfma_f32_16x16x32_bf16 v[4:7], v[176:179], v[160:163], 0
	v_mfma_f32_16x16x32_bf16 v[0:3], v[184:187], v[160:163], 0
	v_mfma_f32_16x16x32_bf16 v[48:51], v[176:179], v[124:127], 0
	v_mfma_f32_16x16x32_bf16 v[52:55], v[184:187], v[124:127], 0
	v_mfma_f32_16x16x32_bf16 v[36:39], v[180:183], v[136:139], v[36:39]
	v_mfma_f32_16x16x32_bf16 v[32:35], v[188:191], v[136:139], v[32:35]
	v_mfma_f32_16x16x32_bf16 v[20:23], v[180:183], v[152:155], v[20:23]
	v_mfma_f32_16x16x32_bf16 v[16:19], v[188:191], v[152:155], v[16:19]
	v_mfma_f32_16x16x32_bf16 v[4:7], v[180:183], v[164:167], v[4:7]
	v_mfma_f32_16x16x32_bf16 v[0:3], v[188:191], v[164:167], v[0:3]
	v_mfma_f32_16x16x32_bf16 v[48:51], v[180:183], v[128:131], v[48:51]
	v_mfma_f32_16x16x32_bf16 v[52:55], v[188:191], v[128:131], v[52:55]
	s_setprio 0
	s_add_i32 s17, 0, 0x18000
	v_add_u32_e32 v76, s17, v237
	s_barrier
	ds_read_b128 v[56:59], v76
	ds_read_b128 v[60:63], v76 offset:1024
	ds_read_b128 v[72:75], v76 offset:2048
	ds_read_b128 v[76:79], v76 offset:3072
	s_add_u32 s14, s14, 0x40000
	s_addc_u32 s15, s15, 0
	s_mov_b32 m0, s48
	v_lshl_add_u64 v[132:133], s[14:15], 0, v[192:193]
	ds_read_b128 v[124:127], v241 offset:32768
	ds_read_b128 v[128:131], v241 offset:33792
	ds_read_b128 v[136:139], v241 offset:34816
	ds_read_b128 v[140:143], v241 offset:35840
	ds_read_b128 v[160:163], v241 offset:36864
	ds_read_b128 v[164:167], v241 offset:37888
	ds_read_b128 v[176:179], v241 offset:38912
	ds_read_b128 v[180:183], v241 offset:39936
	global_load_lds_dwordx4 v[132:133], off
	v_lshl_add_u64 v[132:133], s[14:15], 0, v[196:197]
	s_mov_b32 m0, s49
	s_nop 0
	global_load_lds_dwordx4 v[132:133], off
	s_waitcnt lgkmcnt(8)
	s_barrier
	s_waitcnt lgkmcnt(0)
	s_setprio 1
	s_waitcnt lgkmcnt(0)
	v_mfma_f32_16x16x32_bf16 v[132:135], v[56:59], v[124:127], v[172:175]
	v_mfma_f32_16x16x32_bf16 v[172:175], v[60:63], v[128:131], v[132:135]
	v_mfma_f32_16x16x32_bf16 v[132:135], v[72:75], v[124:127], v[168:171]
	v_mfma_f32_16x16x32_bf16 v[168:171], v[76:79], v[128:131], v[132:135]
	v_mfma_f32_16x16x32_bf16 v[132:135], v[56:59], v[136:139], v[148:151]
	v_mfma_f32_16x16x32_bf16 v[148:151], v[60:63], v[140:143], v[132:135]
	v_mfma_f32_16x16x32_bf16 v[132:135], v[72:75], v[136:139], v[144:147]
	v_mfma_f32_16x16x32_bf16 v[120:123], v[56:59], v[160:163], v[120:123]
	v_mfma_f32_16x16x32_bf16 v[116:119], v[72:75], v[160:163], v[116:119]
	v_mfma_f32_16x16x32_bf16 v[96:99], v[56:59], v[176:179], v[96:99]
	v_mfma_f32_16x16x32_bf16 v[92:95], v[72:75], v[176:179], v[92:95]
	v_mfma_f32_16x16x32_bf16 v[144:147], v[76:79], v[140:143], v[132:135]
	v_mfma_f32_16x16x32_bf16 v[120:123], v[60:63], v[164:167], v[120:123]
	v_mfma_f32_16x16x32_bf16 v[116:119], v[76:79], v[164:167], v[116:119]
	v_mfma_f32_16x16x32_bf16 v[96:99], v[60:63], v[180:183], v[96:99]
	v_mfma_f32_16x16x32_bf16 v[92:95], v[76:79], v[180:183], v[92:95]
	s_setprio 0
	s_barrier
	s_add_i32 s24, 0, 0x1c000
	s_add_u32 s14, s10, 0x80
	v_add_u32_e32 v132, s24, v237
	s_addc_u32 s15, s11, 0
	s_add_i32 s17, s17, s45
	ds_read_b128 v[184:187], v132
	ds_read_b128 v[188:191], v132 offset:1024
	ds_read_b128 v[206:209], v132 offset:2048
	ds_read_b128 v[210:213], v132 offset:3072
	v_lshl_add_u64 v[132:133], s[14:15], 0, v[194:195]
	s_mov_b32 m0, s17
	s_nop 0
	global_load_lds_dwordx4 v[132:133], off
	v_lshl_add_u64 v[132:133], s[14:15], 0, v[198:199]
	s_add_i32 m0, s17, 0x2000
	s_nop 0
	global_load_lds_dwordx4 v[132:133], off
	s_barrier
; #define G8_STAGE(bufoff, gbase, voff) do { const char* _gb = uptr((const char*)(gbase)); _Pragma("unroll") for (int _i = 0; _i < 2; ++_i) \
;         __builtin_amdgcn_global_load_lds((const unsigned*)(_gb + (voff)[_i]), (LAS unsigned*)(lds + (bufoff) + ldsw + _i * 8192), 16, 0, 0); } while (0)
; #define G8_LDA(dst, b, h) do { _Pragma("unroll") for (int m = 0; m < 4; ++m) _Pragma("unroll") for (int k = 0; k < 2; ++k) dst[m][k] = *(const LAS bf16x8*)(lds + G8_SA(b, h) + aoff + m * 2048 + k * 1024); } while (0)
; #define G8_MMA(ai, bj, At, Bt_) do { __builtin_amdgcn_s_setprio(1); _Pragma("unroll") for (int m = 0; m < 4; ++m) _Pragma("unroll") for (int n = 0; n < 2; ++n) _Pragma("unroll") for (int k = 0; k < 2; ++k) \
;         acc[ai][bj][m][n] = __builtin_amdgcn_mfma_f32_16x16x32_bf16(Bt_[n][k], At[m][k], acc[ai][bj][m][n], 0, 0, 0); __builtin_amdgcn_s_setprio(0); } while (0)
; #define G8_WAIT_V(n) asm volatile("s_waitcnt vmcnt(" #n ")" ::: "memory")
; #define G8_WAIT_L(n) asm volatile("s_waitcnt lgkmcnt(" #n ")" ::: "memory")
; #define G8_BAR __builtin_amdgcn_s_barrier()
; #define G8_SCHED __builtin_amdgcn_sched_barrier(0)
;     ...
;             G8_LDA(At, 1, 1); G8_STAGE(G8_SA(1, 0), a3, voffA);
;             G8_BAR; G8_WAIT_L(0); G8_MMA(1, 0, At, B0); G8_BAR; G8_SCHED;
;             G8_STAGE(G8_SB(1, 1), b3 + hstepB, voffB);
;             G8_WAIT_V(6); G8_BAR; G8_MMA(1, 1, At, B1); G8_BAR;
;         }
	s_waitcnt lgkmcnt(0)
	s_setprio 1
	s_waitcnt lgkmcnt(0)
	v_mfma_f32_16x16x32_bf16 v[88:91], v[206:209], v[124:127], v[88:91]
	v_mfma_f32_16x16x32_bf16 v[132:135], v[184:187], v[124:127], v[156:159]
	v_mfma_f32_16x16x32_bf16 v[152:155], v[210:213], v[128:131], v[88:91]
	v_mfma_f32_16x16x32_bf16 v[88:91], v[184:187], v[136:139], v[100:103]
	v_mfma_f32_16x16x32_bf16 v[156:159], v[188:191], v[128:131], v[132:135]
	v_mfma_f32_16x16x32_bf16 v[132:135], v[188:191], v[140:143], v[88:91]
	v_mfma_f32_16x16x32_bf16 v[88:91], v[206:209], v[136:139], v[112:115]
	v_mfma_f32_16x16x32_bf16 v[128:131], v[210:213], v[140:143], v[88:91]
	v_mfma_f32_16x16x32_bf16 v[88:91], v[184:187], v[160:163], v[108:111]
	v_mfma_f32_16x16x32_bf16 v[108:111], v[188:191], v[164:167], v[88:91]
	v_mfma_f32_16x16x32_bf16 v[88:91], v[206:209], v[160:163], v[104:107]
	v_mfma_f32_16x16x32_bf16 v[84:87], v[184:187], v[176:179], v[84:87]
	v_mfma_f32_16x16x32_bf16 v[80:83], v[206:209], v[176:179], v[80:83]
	v_mfma_f32_16x16x32_bf16 v[104:107], v[210:213], v[164:167], v[88:91]
	v_mfma_f32_16x16x32_bf16 v[84:87], v[188:191], v[180:183], v[84:87]
	v_mfma_f32_16x16x32_bf16 v[80:83], v[210:213], v[180:183], v[80:83]
	s_setprio 0
	s_mov_b32 m0, s53
	v_lshl_add_u64 v[176:177], s[12:13], 0, v[192:193]
	s_barrier
	ds_read_b128 v[88:91], v241 offset:49152
	ds_read_b128 v[100:103], v241 offset:50176
	ds_read_b128 v[112:115], v241 offset:51200
	ds_read_b128 v[124:127], v241 offset:52224
	ds_read_b128 v[136:139], v241 offset:53248
	ds_read_b128 v[140:143], v241 offset:54272
	ds_read_b128 v[160:163], v241 offset:55296
	ds_read_b128 v[164:167], v241 offset:56320
	global_load_lds_dwordx4 v[176:177], off
	v_lshl_add_u64 v[176:177], s[12:13], 0, v[196:197]
	s_mov_b32 m0, s33
	s_nop 0
	global_load_lds_dwordx4 v[176:177], off
	s_barrier
	s_waitcnt lgkmcnt(0)
	s_setprio 1
	s_waitcnt lgkmcnt(0)
	v_mfma_f32_16x16x32_bf16 v[68:71], v[56:59], v[88:91], v[68:71]
	v_mfma_f32_16x16x32_bf16 v[64:67], v[72:75], v[88:91], v[64:67]
	v_mfma_f32_16x16x32_bf16 v[44:47], v[56:59], v[112:115], v[44:47]
	v_mfma_f32_16x16x32_bf16 v[40:43], v[72:75], v[112:115], v[40:43]
	v_mfma_f32_16x16x32_bf16 v[28:31], v[56:59], v[136:139], v[28:31]
	v_mfma_f32_16x16x32_bf16 v[24:27], v[72:75], v[136:139], v[24:27]
	v_mfma_f32_16x16x32_bf16 v[12:15], v[56:59], v[160:163], v[12:15]
	v_mfma_f32_16x16x32_bf16 v[8:11], v[72:75], v[160:163], v[8:11]
	v_mfma_f32_16x16x32_bf16 v[68:71], v[60:63], v[100:103], v[68:71]
	v_mfma_f32_16x16x32_bf16 v[64:67], v[76:79], v[100:103], v[64:67]
	v_mfma_f32_16x16x32_bf16 v[44:47], v[60:63], v[124:127], v[44:47]
	v_mfma_f32_16x16x32_bf16 v[40:43], v[76:79], v[124:127], v[40:43]
	v_mfma_f32_16x16x32_bf16 v[28:31], v[60:63], v[140:143], v[28:31]
	v_mfma_f32_16x16x32_bf16 v[24:27], v[76:79], v[140:143], v[24:27]
	v_mfma_f32_16x16x32_bf16 v[12:15], v[60:63], v[164:167], v[12:15]
	v_mfma_f32_16x16x32_bf16 v[8:11], v[76:79], v[164:167], v[8:11]
	s_setprio 0
	s_barrier
	s_add_u32 s10, s10, 0x40080
	s_addc_u32 s11, s11, 0
	s_add_i32 s12, s24, s45
	v_lshl_add_u64 v[56:57], s[10:11], 0, v[194:195]
	s_mov_b32 m0, s12
	s_nop 0
	global_load_lds_dwordx4 v[56:57], off
	v_lshl_add_u64 v[56:57], s[10:11], 0, v[198:199]
	s_add_i32 m0, s12, 0x2000
	s_nop 0
	global_load_lds_dwordx4 v[56:57], off
	s_waitcnt vmcnt(6)
	s_barrier
	s_setprio 1
	v_mfma_f32_16x16x32_bf16 v[48:51], v[184:187], v[88:91], v[48:51]
	v_mfma_f32_16x16x32_bf16 v[60:63], v[188:191], v[100:103], v[48:51]
	v_mfma_f32_16x16x32_bf16 v[48:51], v[206:209], v[88:91], v[52:55]
	v_mfma_f32_16x16x32_bf16 v[36:39], v[184:187], v[112:115], v[36:39]
	v_mfma_f32_16x16x32_bf16 v[32:35], v[206:209], v[112:115], v[32:35]
	v_mfma_f32_16x16x32_bf16 v[20:23], v[184:187], v[136:139], v[20:23]
	v_mfma_f32_16x16x32_bf16 v[16:19], v[206:209], v[136:139], v[16:19]
	v_mfma_f32_16x16x32_bf16 v[4:7], v[184:187], v[160:163], v[4:7]
	v_mfma_f32_16x16x32_bf16 v[0:3], v[206:209], v[160:163], v[0:3]
	v_mfma_f32_16x16x32_bf16 v[56:59], v[210:213], v[100:103], v[48:51]
	v_mfma_f32_16x16x32_bf16 v[36:39], v[188:191], v[124:127], v[36:39]
	v_mfma_f32_16x16x32_bf16 v[32:35], v[210:213], v[124:127], v[32:35]
	v_mfma_f32_16x16x32_bf16 v[20:23], v[188:191], v[140:143], v[20:23]
	v_mfma_f32_16x16x32_bf16 v[16:19], v[210:213], v[140:143], v[16:19]
	v_mfma_f32_16x16x32_bf16 v[4:7], v[188:191], v[164:167], v[4:7]
	v_mfma_f32_16x16x32_bf16 v[0:3], v[210:213], v[164:167], v[0:3]
	s_setprio 0
	s_add_i32 s16, s16, 2
	s_add_u32 s7, s7, 0x100
	s_addc_u32 s9, s9, 0
	s_add_u32 s2, s2, 0x100
	s_addc_u32 s3, s3, 0
	s_cmp_gt_u32 s16, 13
	s_barrier
